# attention K/V tile LDS-DMA: uniform bases in SGPR pairs advanced by SALU, 32-bit lane offsets (8 fewer 64-bit VALU adds per step)
# speedup vs baseline: 1.0031x; 1.0031x over previous
.LBB0_842:
	s_or_b64 exec, exec, s[0:1]
	v_readfirstlane_b32 s98, v0
	v_readfirstlane_b32 s99, v1
	v_readfirstlane_b32 s100, v2
	v_readfirstlane_b32 s101, v3
	v_mov_b32_e32 v129, v113
	v_mul_u32_u24_e32 v5, v4, v151
	v_lshl_add_u64 v[6:7], v[0:1], 0, v[128:129]
	v_mov_b32_e32 v131, v113
	v_lshlrev_b32_e32 v8, 1, v5
	v_mov_b32_e32 v9, v113
	v_readfirstlane_b32 s0, v155
	v_add_u32_e32 v5, 0x4000, v155
	v_lshl_add_u64 v[6:7], v[6:7], 0, v[130:131]
	v_lshl_add_u64 v[10:11], v[2:3], 0, v[8:9]
	v_mov_b32_e32 v133, v113
	s_mov_b32 m0, s0
	v_readfirstlane_b32 s0, v5
	v_add_u32_e32 v5, 0x1000, v155
	v_lshl_add_u64 v[10:11], v[10:11], 0, v[132:133]
	global_load_lds_dwordx4 v[6:7], off
	s_mov_b32 m0, s0
	v_readfirstlane_b32 s0, v5
	v_add_u32_e32 v5, 0x5000, v155
	global_load_lds_dwordx4 v[10:11], off
	v_lshl_add_u64 v[12:13], v[6:7], 0, s[34:35]
	s_mov_b32 m0, s0
	v_lshlrev_b32_e32 v112, 6, v4
	v_readfirstlane_b32 s0, v5
	v_add_u32_e32 v5, 0x2000, v155
	global_load_lds_dwordx4 v[12:13], off
	v_lshl_add_u64 v[10:11], v[10:11], 0, v[112:113]
	s_mov_b32 m0, s0
	v_readfirstlane_b32 s0, v5
	v_add_u32_e32 v5, 0x6000, v155
	global_load_lds_dwordx4 v[10:11], off
	v_lshl_add_u64 v[12:13], v[6:7], 0, s[36:37]
	s_mov_b32 m0, s0
	v_readfirstlane_b32 s0, v5
	v_add_u32_e32 v5, 0x3000, v155
	global_load_lds_dwordx4 v[12:13], off
	v_lshl_add_u64 v[10:11], v[10:11], 0, v[112:113]
	s_mov_b32 m0, s0
	v_readfirstlane_b32 s0, v5
	v_add_u32_e32 v5, 0x7000, v155
	global_load_lds_dwordx4 v[10:11], off
	v_lshl_add_u64 v[6:7], v[6:7], 0, s[38:39]
	s_mov_b32 m0, s0
	v_readfirstlane_b32 s0, v5
	global_load_lds_dwordx4 v[6:7], off
	v_lshl_add_u64 v[6:7], v[10:11], 0, v[112:113]
	s_mov_b32 m0, s0
	v_lshl_add_u64 v[140:141], v[0:1], 0, v[120:121]
	global_load_lds_dwordx4 v[6:7], off
	v_lshl_add_u64 v[0:1], v[2:3], 0, v[122:123]
	v_mov_b32_e32 v14, v113
	v_mov_b32_e32 v15, v113
	v_lshl_add_u64 v[142:143], v[0:1], 0, v[8:9]
	v_lshlrev_b32_e32 v146, 7, v4
	v_mul_hi_u32_u24_e32 v149, 0xc0, v4
	v_mul_u32_u24_e32 v148, 0xc0, v4
	v_mov_b32_e32 v0, v113
	v_mov_b32_e32 v1, v113
	v_mov_b32_e32 v2, v113
	v_mov_b32_e32 v3, v113
	v_mov_b32_e32 v4, v113
	v_mov_b32_e32 v5, v113
	v_mov_b32_e32 v6, v113
	v_mov_b32_e32 v7, v113
	v_mov_b32_e32 v8, v113
	v_mov_b32_e32 v10, v113
	v_mov_b32_e32 v11, v113
	v_mov_b32_e32 v12, v113
	v_mov_b32_e32 v13, v113
	v_mov_b64_e32 v[30:31], v[14:15]
	v_mov_b64_e32 v[46:47], v[14:15]
	v_mov_b64_e32 v[62:63], v[14:15]
	s_xor_b64 s[46:47], s[8:9], -1
	v_cmp_lt_u32_e64 s[8:9], v145, v127
	v_cmp_ge_u32_e64 s[10:11], v145, v127
	s_mov_b32 s33, 1
	v_mov_b32_e32 v147, v113
	v_lshlrev_b32_e32 v129, 6, v137
	v_mov_b64_e32 v[28:29], v[12:13]
	v_mov_b64_e32 v[26:27], v[10:11]
	v_mov_b64_e32 v[24:25], v[8:9]
	v_mov_b64_e32 v[22:23], v[6:7]
	v_mov_b64_e32 v[20:21], v[4:5]
	v_mov_b64_e32 v[18:19], v[2:3]
	v_mov_b64_e32 v[16:17], v[0:1]
	v_mov_b64_e32 v[44:45], v[12:13]
	v_mov_b64_e32 v[42:43], v[10:11]
	v_mov_b64_e32 v[40:41], v[8:9]
	v_mov_b64_e32 v[38:39], v[6:7]
	v_mov_b64_e32 v[36:37], v[4:5]
	v_mov_b64_e32 v[34:35], v[2:3]
	v_mov_b64_e32 v[32:33], v[0:1]
	v_mov_b64_e32 v[60:61], v[12:13]
	v_mov_b64_e32 v[58:59], v[10:11]
	v_mov_b64_e32 v[56:57], v[8:9]
	v_mov_b64_e32 v[54:55], v[6:7]
	v_mov_b64_e32 v[52:53], v[4:5]
	v_mov_b64_e32 v[50:51], v[2:3]
	v_mov_b64_e32 v[48:49], v[0:1]
	v_mov_b32_e32 v131, 0
	s_waitcnt vmcnt(0)
	v_subrev_u32_e32 v200, s98, v140
	v_subrev_u32_e32 v204, s100, v142
	v_add_u32_e32 v201, s34, v200
	v_add_u32_e32 v202, s36, v200
	v_add_u32_e32 v203, s38, v200
	v_add_u32_e32 v205, v204, v112
	v_add_u32_e32 v206, v204, v146
	v_add_u32_e32 v207, v204, v148
	v_readfirstlane_b32 s60, v155
	v_xor_b32_e32 v232, 0x80000000, v125
	v_mov_b32_e32 v233, v232
	v_mov_b32_e32 v234, v232
	v_mov_b32_e32 v235, v232
	v_mov_b32_e32 v236, v232
	v_mov_b32_e32 v237, v232
	v_mov_b32_e32 v238, v232
	v_mov_b32_e32 v239, v232
	v_mov_b32_e32 v240, v232
	v_mov_b32_e32 v241, v232
	v_mov_b32_e32 v242, v232
	v_mov_b32_e32 v243, v232
	v_mov_b32_e32 v244, v232
	v_mov_b32_e32 v245, v232
	v_mov_b32_e32 v246, v232
	v_mov_b32_e32 v247, v232
	s_branch .LBB0_845

.LBB0_844:
	s_or_b64 exec, exec, s[48:49]
	s_add_i32 s33, s33, 1
	v_cmp_eq_u32_e32 vcc, v129, v133
	s_or_b64 s[44:45], vcc, s[44:45]
	v_mov_b32_e32 v172, v133
	s_andn2_b64 exec, exec, s[44:45]
	s_cbranch_execz .LBB0_855
.LBB0_845:
	s_waitcnt vmcnt(0)
	s_waitcnt lgkmcnt(0)
	s_add_i32 s0, s33, -1
	s_and_b32 s50, s0, 1
	v_cmp_lt_u32_e32 vcc, s33, v137
	s_barrier
	s_and_saveexec_b64 s[0:1], vcc
	s_cbranch_execz .LBB0_847
	s_lshl_b32 s48, s50, 15
	s_xor_b32 s48, s48, 0x8000
	s_add_u32 s48, s48, s60
	s_mov_b32 m0, s48
	s_nop 0
	global_load_lds_dwordx4 v200, s[98:99]
	s_add_u32 m0, s48, 0x4000
	s_nop 0
	global_load_lds_dwordx4 v204, s[100:101]
	s_add_u32 m0, s48, 0x1000
	s_nop 0
	global_load_lds_dwordx4 v201, s[98:99]
	s_add_u32 m0, s48, 0x5000
	s_nop 0
	global_load_lds_dwordx4 v205, s[100:101]
	s_add_u32 m0, s48, 0x2000
	s_nop 0
	global_load_lds_dwordx4 v202, s[98:99]
	s_add_u32 m0, s48, 0x6000
	s_nop 0
	global_load_lds_dwordx4 v206, s[100:101]
	s_add_u32 m0, s48, 0x3000
	s_nop 0
	global_load_lds_dwordx4 v203, s[98:99]
	s_add_u32 m0, s48, 0x7000
	s_add_u32 s98, s98, s28
	global_load_lds_dwordx4 v207, s[100:101]
	s_addc_u32 s99, s99, s29
	s_add_u32 s100, s100, s40
	s_addc_u32 s101, s101, s41
